# scan phase: the retention wave (which has slack) pauses s_sleep 6 per 32-step body, leaving LDS / issue bandwidth to the GDN and HGRN waves that end the phase
# baseline (speedup 1.0000x reference)
.Lls0_8_noflush:
	s_waitcnt lgkmcnt(2)
	ds_read_b128 v[22:25], v0 offset:4352
	ds_read_b128 v[26:29], v0 offset:4368
	ds_read_b128 v[46:49], v0 offset:6400
	ds_read_b128 v[50:53], v0 offset:6416
	ds_read_b32 v30, v1 offset:8448
	v_fmac_f32_e32 v8, v38, v32
	v_fmac_f32_e32 v9, v39, v32
	v_mul_f32_e32 v102, v54, v8
	v_fmac_f32_e32 v10, v40, v32
	v_fmac_f32_e32 v102, v55, v9
	v_fmac_f32_e32 v11, v41, v32
	v_fmac_f32_e32 v102, v56, v10
	v_fmac_f32_e32 v12, v42, v32
	v_fmac_f32_e32 v102, v57, v11
	v_fmac_f32_e32 v13, v43, v32
	v_fmac_f32_e32 v102, v58, v12
	v_fmac_f32_e32 v14, v44, v32
	v_fmac_f32_e32 v102, v59, v13
	v_fmac_f32_e32 v15, v45, v32
	v_fmac_f32_e32 v102, v60, v14
	v_fmac_f32_e32 v102, v61, v15
	ds_write_b32 v118, v102 offset:10496
	s_waitcnt lgkmcnt(1)
	ds_read_b128 v[38:41], v0 offset:4608
	ds_read_b128 v[42:45], v0 offset:4624
	ds_read_b128 v[54:57], v0 offset:6656
	ds_read_b128 v[58:61], v0 offset:6672
	ds_read_b32 v32, v1 offset:8480
	v_fmac_f32_e32 v8, v22, v30
	v_fmac_f32_e32 v9, v23, v30
	v_mul_f32_e32 v36, v46, v8
	s_waitcnt vmcnt(10)
	v_fmac_f32_e32 v10, v24, v30
	v_fmac_f32_e32 v36, v47, v9
	v_fmac_f32_e32 v11, v25, v30
	v_lshlrev_b32_e32 v94, 16, v82
	v_fmac_f32_e32 v36, v48, v10
	v_fmac_f32_e32 v12, v26, v30
	v_fmac_f32_e32 v36, v49, v11
	v_and_b32_e32 v95, 0xffff0000, v82
	v_fmac_f32_e32 v13, v27, v30
	v_fmac_f32_e32 v36, v50, v12
	v_fmac_f32_e32 v14, v28, v30
	v_lshlrev_b32_e32 v96, 16, v83
	v_fmac_f32_e32 v36, v51, v13
	v_fmac_f32_e32 v15, v29, v30
	v_fmac_f32_e32 v36, v52, v14
	v_and_b32_e32 v97, 0xffff0000, v83
	v_fmac_f32_e32 v36, v53, v15
	ds_write_b32 v118, v36 offset:10752
	ds_write_b128 v2, v[94:97] offset:0
	v_lshlrev_b32_e32 v98, 16, v84
	s_waitcnt lgkmcnt(2)
	ds_read_b128 v[22:25], v0 offset:4864
	ds_read_b128 v[26:29], v0 offset:4880
	ds_read_b128 v[46:49], v0 offset:6912
	ds_read_b128 v[50:53], v0 offset:6928
	ds_read_b32 v30, v1 offset:8512
	v_fmac_f32_e32 v8, v38, v32
	v_fmac_f32_e32 v9, v39, v32
	v_mul_f32_e32 v102, v54, v8
	v_and_b32_e32 v99, 0xffff0000, v84
	v_fmac_f32_e32 v10, v40, v32
	v_fmac_f32_e32 v102, v55, v9
	v_fmac_f32_e32 v11, v41, v32
	v_lshlrev_b32_e32 v100, 16, v85
	v_fmac_f32_e32 v102, v56, v10
	v_fmac_f32_e32 v12, v42, v32
	v_fmac_f32_e32 v102, v57, v11
	v_and_b32_e32 v101, 0xffff0000, v85
	v_fmac_f32_e32 v13, v43, v32
	v_fmac_f32_e32 v102, v58, v12
	v_fmac_f32_e32 v14, v44, v32
	ds_write_b128 v2, v[98:101] offset:16
	v_fmac_f32_e32 v102, v59, v13
	v_fmac_f32_e32 v15, v45, v32
	v_fmac_f32_e32 v102, v60, v14
	v_lshlrev_b32_e32 v94, 16, v78
	v_fmac_f32_e32 v102, v61, v15
	ds_write_b32 v118, v102 offset:11008
	v_and_b32_e32 v95, 0xffff0000, v78
	v_lshlrev_b32_e32 v96, 16, v79
	s_waitcnt lgkmcnt(2)
	ds_read_b128 v[38:41], v0 offset:5120
	ds_read_b128 v[42:45], v0 offset:5136
	ds_read_b128 v[54:57], v0 offset:7168
	ds_read_b128 v[58:61], v0 offset:7184
	ds_read_b32 v32, v1 offset:8544
	v_fmac_f32_e32 v8, v22, v30
	v_fmac_f32_e32 v9, v23, v30
	v_mul_f32_e32 v36, v46, v8
	v_and_b32_e32 v97, 0xffff0000, v79
	v_fmac_f32_e32 v10, v24, v30
	v_fmac_f32_e32 v36, v47, v9
	v_fmac_f32_e32 v11, v25, v30
	ds_write_b128 v2, v[94:97] offset:2048
	v_fmac_f32_e32 v36, v48, v10
	v_fmac_f32_e32 v12, v26, v30
	v_fmac_f32_e32 v36, v49, v11
	v_lshlrev_b32_e32 v98, 16, v80
	v_fmac_f32_e32 v13, v27, v30
	v_fmac_f32_e32 v36, v50, v12
	v_fmac_f32_e32 v14, v28, v30
	v_and_b32_e32 v99, 0xffff0000, v80
	v_fmac_f32_e32 v36, v51, v13
	v_fmac_f32_e32 v15, v29, v30
	v_fmac_f32_e32 v36, v52, v14
	v_lshlrev_b32_e32 v100, 16, v81
	v_fmac_f32_e32 v36, v53, v15
	ds_write_b32 v118, v36 offset:11264
	v_and_b32_e32 v101, 0xffff0000, v81
	ds_write_b128 v2, v[98:101] offset:2064
	s_waitcnt lgkmcnt(3)
	ds_read_b128 v[22:25], v0 offset:5376
	ds_read_b128 v[26:29], v0 offset:5392
	ds_read_b128 v[46:49], v0 offset:7424
	ds_read_b128 v[50:53], v0 offset:7440
	ds_read_b32 v30, v1 offset:8576
	v_fmac_f32_e32 v8, v38, v32
	v_fmac_f32_e32 v9, v39, v32
	v_mul_f32_e32 v102, v54, v8
	s_waitcnt vmcnt(9)
	v_fmac_f32_e32 v10, v40, v32
	v_fmac_f32_e32 v102, v55, v9
	v_fmac_f32_e32 v11, v41, v32
	v_lshlrev_b32_e32 v34, 16, v34
	v_fmac_f32_e32 v102, v56, v10
	v_fmac_f32_e32 v12, v42, v32
	v_fmac_f32_e32 v102, v57, v11
	v_mul_f32_e32 v34, v105, v34
	v_fmac_f32_e32 v13, v43, v32
	v_fmac_f32_e32 v102, v58, v12
	v_fmac_f32_e32 v14, v44, v32
	s_nop 0
	v_fmac_f32_e32 v102, v59, v13
	v_fmac_f32_e32 v15, v45, v32
	v_fmac_f32_e32 v102, v60, v14
	ds_write_b32 v4, v34 offset:4096
	v_fmac_f32_e32 v102, v61, v15
	ds_write_b32 v118, v102 offset:11520
	s_waitcnt lgkmcnt(2)
	ds_read_b128 v[38:41], v0 offset:5632
	ds_read_b128 v[42:45], v0 offset:5648
	ds_read_b128 v[54:57], v0 offset:7680
	ds_read_b128 v[58:61], v0 offset:7696
	ds_read_b32 v32, v1 offset:8608
	v_fmac_f32_e32 v8, v22, v30
	v_fmac_f32_e32 v9, v23, v30
	v_mul_f32_e32 v36, v46, v8
	global_load_dwordx4 v[78:81], v5, s[94:95]
	global_load_dwordx4 v[82:85], v5, s[94:95] offset:512
	global_load_ushort v34, v6, s[94:95]
	v_add_u32_e32 v5, 0x6800, v5
	v_add_u32_e32 v6, 0x10000, v6
	v_fmac_f32_e32 v10, v24, v30
	v_fmac_f32_e32 v36, v47, v9
	v_fmac_f32_e32 v11, v25, v30
	ds_read_b128 v[124:127], v119 offset:8704
	v_fmac_f32_e32 v36, v48, v10
	v_fmac_f32_e32 v12, v26, v30
	v_fmac_f32_e32 v36, v49, v11
	ds_read_b128 v[128:131], v120 offset:8704
	v_fmac_f32_e32 v13, v27, v30
	v_fmac_f32_e32 v36, v50, v12
	v_fmac_f32_e32 v14, v28, v30
	v_fmac_f32_e32 v36, v51, v13
	v_fmac_f32_e32 v15, v29, v30
	v_fmac_f32_e32 v36, v52, v14
	v_fmac_f32_e32 v36, v53, v15
	ds_write_b32 v118, v36 offset:11776
	s_waitcnt lgkmcnt(3)
	ds_read_b128 v[22:25], v0 offset:5888
	ds_read_b128 v[26:29], v0 offset:5904
	ds_read_b128 v[46:49], v0 offset:7936
	ds_read_b128 v[50:53], v0 offset:7952
	ds_read_b32 v30, v1 offset:8640
	v_fmac_f32_e32 v8, v38, v32
	v_fmac_f32_e32 v9, v39, v32
	v_mul_f32_e32 v102, v54, v8
	v_fmac_f32_e32 v10, v40, v32
	v_fmac_f32_e32 v102, v55, v9
	v_fmac_f32_e32 v11, v41, v32
	v_fmac_f32_e32 v102, v56, v10
	v_fmac_f32_e32 v12, v42, v32
	v_fmac_f32_e32 v102, v57, v11
	v_fmac_f32_e32 v13, v43, v32
	v_fmac_f32_e32 v102, v58, v12
	v_fmac_f32_e32 v14, v44, v32
	v_fmac_f32_e32 v102, v59, v13
	v_fmac_f32_e32 v15, v45, v32
	v_fmac_f32_e32 v102, v60, v14
	v_fmac_f32_e32 v102, v61, v15
	ds_write_b32 v118, v102 offset:12032
	s_waitcnt lgkmcnt(1)
	ds_read_b128 v[38:41], v0 offset:6144
	ds_read_b128 v[42:45], v0 offset:6160
	ds_read_b128 v[54:57], v0 offset:8192
	ds_read_b128 v[58:61], v0 offset:8208
	ds_read_b32 v32, v1 offset:8672
	v_fmac_f32_e32 v8, v22, v30
	v_fmac_f32_e32 v9, v23, v30
	v_mul_f32_e32 v36, v46, v8
	s_waitcnt lgkmcnt(12)
	v_fmac_f32_e32 v10, v24, v30
	v_fmac_f32_e32 v36, v47, v9
	v_fmac_f32_e32 v11, v25, v30
	v_add_f32_e32 v124, v124, v128
	v_fmac_f32_e32 v36, v48, v10
	v_fmac_f32_e32 v12, v26, v30
	v_fmac_f32_e32 v36, v49, v11
	v_add_f32_e32 v125, v125, v129
	v_fmac_f32_e32 v13, v27, v30
	v_fmac_f32_e32 v36, v50, v12
	v_fmac_f32_e32 v14, v28, v30
	v_add_f32_e32 v126, v126, v130
	v_fmac_f32_e32 v36, v51, v13
	v_fmac_f32_e32 v15, v29, v30
	v_fmac_f32_e32 v36, v52, v14
	v_add_f32_e32 v127, v127, v131
	v_fmac_f32_e32 v36, v53, v15
	ds_write_b32 v118, v36 offset:12288
	v_add_f32_e32 v124, v124, v125
	v_add_f32_e32 v126, v126, v127
	v_add_f32_e32 v124, v124, v126
	v_mul_f32_e32 v124, v107, v124
	v_cvt_pk_bf16_f32 v21, v124, v124
	ds_write_b16 v112, v21 offset:13312
	s_waitcnt lgkmcnt(2)
	ds_read_b128 v[22:25], v0 offset:0
	ds_read_b128 v[26:29], v0 offset:16
	ds_read_b128 v[46:49], v0 offset:2048
	ds_read_b128 v[50:53], v0 offset:2064
	ds_read_b32 v30, v1 offset:4096
	v_fmac_f32_e32 v8, v38, v32
	v_fmac_f32_e32 v9, v39, v32
	v_mul_f32_e32 v102, v54, v8
	v_fmac_f32_e32 v10, v40, v32
	v_fmac_f32_e32 v102, v55, v9
	v_fmac_f32_e32 v11, v41, v32
	v_fmac_f32_e32 v102, v56, v10
	v_fmac_f32_e32 v12, v42, v32
	v_fmac_f32_e32 v102, v57, v11
	v_fmac_f32_e32 v13, v43, v32
	v_fmac_f32_e32 v102, v58, v12
	v_fmac_f32_e32 v14, v44, v32
	v_fmac_f32_e32 v102, v59, v13
	v_fmac_f32_e32 v15, v45, v32
	v_fmac_f32_e32 v102, v60, v14
	v_fmac_f32_e32 v102, v61, v15
	ds_write_b32 v118, v102 offset:12544
	s_waitcnt lgkmcnt(1)
	ds_read_b128 v[38:41], v0 offset:256
	ds_read_b128 v[42:45], v0 offset:272
	ds_read_b128 v[54:57], v0 offset:2304
	ds_read_b128 v[58:61], v0 offset:2320
	ds_read_b32 v32, v1 offset:4128
	v_fmac_f32_e32 v8, v22, v30
	v_fmac_f32_e32 v9, v23, v30
	v_mul_f32_e32 v36, v46, v8
	s_waitcnt vmcnt(10)
	v_fmac_f32_e32 v10, v24, v30
	v_fmac_f32_e32 v36, v47, v9
	v_fmac_f32_e32 v11, v25, v30
	v_lshlrev_b32_e32 v94, 16, v90
	v_fmac_f32_e32 v36, v48, v10
	v_fmac_f32_e32 v12, v26, v30
	v_fmac_f32_e32 v36, v49, v11
	v_and_b32_e32 v95, 0xffff0000, v90
	v_fmac_f32_e32 v13, v27, v30
	v_fmac_f32_e32 v36, v50, v12
	v_fmac_f32_e32 v14, v28, v30
	v_lshlrev_b32_e32 v96, 16, v91
	v_fmac_f32_e32 v36, v51, v13
	v_fmac_f32_e32 v15, v29, v30
	v_fmac_f32_e32 v36, v52, v14
	v_and_b32_e32 v97, 0xffff0000, v91
	v_fmac_f32_e32 v36, v53, v15
	ds_write_b32 v118, v36 offset:8704
	ds_write_b128 v2, v[94:97] offset:4352
	v_lshlrev_b32_e32 v98, 16, v92
	s_waitcnt lgkmcnt(2)
	ds_read_b128 v[22:25], v0 offset:512
	ds_read_b128 v[26:29], v0 offset:528
	ds_read_b128 v[46:49], v0 offset:2560
	ds_read_b128 v[50:53], v0 offset:2576
	ds_read_b32 v30, v1 offset:4160
	v_fmac_f32_e32 v8, v38, v32
	v_fmac_f32_e32 v9, v39, v32
	v_mul_f32_e32 v102, v54, v8
	v_and_b32_e32 v99, 0xffff0000, v92
	v_fmac_f32_e32 v10, v40, v32
	v_fmac_f32_e32 v102, v55, v9
	v_fmac_f32_e32 v11, v41, v32
	v_lshlrev_b32_e32 v100, 16, v93
	v_fmac_f32_e32 v102, v56, v10
	v_fmac_f32_e32 v12, v42, v32
	v_fmac_f32_e32 v102, v57, v11
	v_and_b32_e32 v101, 0xffff0000, v93
	v_fmac_f32_e32 v13, v43, v32
	v_fmac_f32_e32 v102, v58, v12
	v_fmac_f32_e32 v14, v44, v32
	ds_write_b128 v2, v[98:101] offset:4368
	v_fmac_f32_e32 v102, v59, v13
	v_fmac_f32_e32 v15, v45, v32
	v_fmac_f32_e32 v102, v60, v14
	v_lshlrev_b32_e32 v94, 16, v86
	v_fmac_f32_e32 v102, v61, v15
	ds_write_b32 v118, v102 offset:8960
	v_and_b32_e32 v95, 0xffff0000, v86
	v_lshlrev_b32_e32 v96, 16, v87
	s_waitcnt lgkmcnt(2)
	ds_read_b128 v[38:41], v0 offset:768
	ds_read_b128 v[42:45], v0 offset:784
	ds_read_b128 v[54:57], v0 offset:2816
	ds_read_b128 v[58:61], v0 offset:2832
	ds_read_b32 v32, v1 offset:4192
	v_fmac_f32_e32 v8, v22, v30
	v_fmac_f32_e32 v9, v23, v30
	v_mul_f32_e32 v36, v46, v8
	v_and_b32_e32 v97, 0xffff0000, v87
	v_fmac_f32_e32 v10, v24, v30
	v_fmac_f32_e32 v36, v47, v9
	v_fmac_f32_e32 v11, v25, v30
	ds_write_b128 v2, v[94:97] offset:6400
	v_fmac_f32_e32 v36, v48, v10
	v_fmac_f32_e32 v12, v26, v30
	v_fmac_f32_e32 v36, v49, v11
	v_lshlrev_b32_e32 v98, 16, v88
	v_fmac_f32_e32 v13, v27, v30
	v_fmac_f32_e32 v36, v50, v12
	v_fmac_f32_e32 v14, v28, v30
	v_and_b32_e32 v99, 0xffff0000, v88
	v_fmac_f32_e32 v36, v51, v13
	v_fmac_f32_e32 v15, v29, v30
	v_fmac_f32_e32 v36, v52, v14
	v_lshlrev_b32_e32 v100, 16, v89
	v_fmac_f32_e32 v36, v53, v15
	ds_write_b32 v118, v36 offset:9216
	v_and_b32_e32 v101, 0xffff0000, v89
	ds_write_b128 v2, v[98:101] offset:6416
	s_waitcnt lgkmcnt(3)
	ds_read_b128 v[22:25], v0 offset:1024
	ds_read_b128 v[26:29], v0 offset:1040
	ds_read_b128 v[46:49], v0 offset:3072
	ds_read_b128 v[50:53], v0 offset:3088
	ds_read_b32 v30, v1 offset:4224
	v_fmac_f32_e32 v8, v38, v32
	v_fmac_f32_e32 v9, v39, v32
	v_mul_f32_e32 v102, v54, v8
	s_waitcnt vmcnt(9)
	v_fmac_f32_e32 v10, v40, v32
	v_fmac_f32_e32 v102, v55, v9
	v_fmac_f32_e32 v11, v41, v32
	v_lshlrev_b32_e32 v35, 16, v35
	v_fmac_f32_e32 v102, v56, v10
	v_fmac_f32_e32 v12, v42, v32
	v_fmac_f32_e32 v102, v57, v11
	v_mul_f32_e32 v35, v106, v35
	v_fmac_f32_e32 v13, v43, v32
	v_fmac_f32_e32 v102, v58, v12
	v_fmac_f32_e32 v14, v44, v32
	s_nop 0
	v_fmac_f32_e32 v102, v59, v13
	v_fmac_f32_e32 v15, v45, v32
	v_fmac_f32_e32 v102, v60, v14
	ds_write_b32 v4, v35 offset:8448
	v_fmac_f32_e32 v102, v61, v15
	ds_write_b32 v118, v102 offset:9472
	s_waitcnt lgkmcnt(2)
	ds_read_b128 v[38:41], v0 offset:1280
	ds_read_b128 v[42:45], v0 offset:1296
	ds_read_b128 v[54:57], v0 offset:3328
	ds_read_b128 v[58:61], v0 offset:3344
	ds_read_b32 v32, v1 offset:4256
	v_fmac_f32_e32 v8, v22, v30
	v_fmac_f32_e32 v9, v23, v30
	v_mul_f32_e32 v36, v46, v8
	global_load_dwordx4 v[86:89], v5, s[94:95]
	global_load_dwordx4 v[90:93], v5, s[94:95] offset:512
	global_load_ushort v35, v6, s[94:95]
	v_add_u32_e32 v5, 0x6800, v5
	v_add_u32_e32 v6, 0x10000, v6
	v_fmac_f32_e32 v10, v24, v30
	v_fmac_f32_e32 v36, v47, v9
	v_fmac_f32_e32 v11, v25, v30
	ds_read_b128 v[124:127], v119 offset:10752
	v_fmac_f32_e32 v36, v48, v10
	v_fmac_f32_e32 v12, v26, v30
	v_fmac_f32_e32 v36, v49, v11
	ds_read_b128 v[128:131], v120 offset:10752
	v_fmac_f32_e32 v13, v27, v30
	v_fmac_f32_e32 v36, v50, v12
	v_fmac_f32_e32 v14, v28, v30
	v_fmac_f32_e32 v36, v51, v13
	v_fmac_f32_e32 v15, v29, v30
	v_fmac_f32_e32 v36, v52, v14
	v_fmac_f32_e32 v36, v53, v15
	ds_write_b32 v118, v36 offset:9728
	s_waitcnt lgkmcnt(3)
	ds_read_b128 v[22:25], v0 offset:1536
	ds_read_b128 v[26:29], v0 offset:1552
	ds_read_b128 v[46:49], v0 offset:3584
	ds_read_b128 v[50:53], v0 offset:3600
	ds_read_b32 v30, v1 offset:4288
	v_fmac_f32_e32 v8, v38, v32
	v_fmac_f32_e32 v9, v39, v32
	v_mul_f32_e32 v102, v54, v8
	v_fmac_f32_e32 v10, v40, v32
	v_fmac_f32_e32 v102, v55, v9
	v_fmac_f32_e32 v11, v41, v32
	v_fmac_f32_e32 v102, v56, v10
	v_fmac_f32_e32 v12, v42, v32
	v_fmac_f32_e32 v102, v57, v11
	v_fmac_f32_e32 v13, v43, v32
	v_fmac_f32_e32 v102, v58, v12
	v_fmac_f32_e32 v14, v44, v32
	v_fmac_f32_e32 v102, v59, v13
	v_fmac_f32_e32 v15, v45, v32
	v_fmac_f32_e32 v102, v60, v14
	v_fmac_f32_e32 v102, v61, v15
	ds_write_b32 v118, v102 offset:9984
	s_waitcnt lgkmcnt(1)
	ds_read_b128 v[38:41], v0 offset:1792
	ds_read_b128 v[42:45], v0 offset:1808
	ds_read_b128 v[54:57], v0 offset:3840
	ds_read_b128 v[58:61], v0 offset:3856
	ds_read_b32 v32, v1 offset:4320
	v_fmac_f32_e32 v8, v22, v30
	v_fmac_f32_e32 v9, v23, v30
	v_mul_f32_e32 v36, v46, v8
	s_waitcnt lgkmcnt(12)
	v_fmac_f32_e32 v10, v24, v30
	v_fmac_f32_e32 v36, v47, v9
	v_fmac_f32_e32 v11, v25, v30
	v_add_f32_e32 v124, v124, v128
	v_fmac_f32_e32 v36, v48, v10
	v_fmac_f32_e32 v12, v26, v30
	v_fmac_f32_e32 v36, v49, v11
	v_add_f32_e32 v125, v125, v129
	v_fmac_f32_e32 v13, v27, v30
	v_fmac_f32_e32 v36, v50, v12
	v_fmac_f32_e32 v14, v28, v30
	v_add_f32_e32 v126, v126, v130
	v_fmac_f32_e32 v36, v51, v13
	v_fmac_f32_e32 v15, v29, v30
	v_fmac_f32_e32 v36, v52, v14
	v_add_f32_e32 v127, v127, v131
	v_fmac_f32_e32 v36, v53, v15
	ds_write_b32 v118, v36 offset:10240
	v_add_f32_e32 v124, v124, v125
	v_add_f32_e32 v126, v126, v127
	v_add_f32_e32 v124, v124, v126
	v_mul_f32_e32 v124, v108, v124
	v_cvt_pk_bf16_f32 v21, v124, v124
	ds_write_b16 v112, v21 offset:13440
	s_waitcnt lgkmcnt(2)
	ds_read_b128 v[22:25], v0 offset:4352
	ds_read_b128 v[26:29], v0 offset:4368
	ds_read_b128 v[46:49], v0 offset:6400
	ds_read_b128 v[50:53], v0 offset:6416
	ds_read_b32 v30, v1 offset:8448
	v_fmac_f32_e32 v8, v38, v32
	v_fmac_f32_e32 v9, v39, v32
	v_mul_f32_e32 v102, v54, v8
	v_fmac_f32_e32 v10, v40, v32
	v_fmac_f32_e32 v102, v55, v9
	v_fmac_f32_e32 v11, v41, v32
	v_fmac_f32_e32 v102, v56, v10
	v_fmac_f32_e32 v12, v42, v32
	v_fmac_f32_e32 v102, v57, v11
	v_fmac_f32_e32 v13, v43, v32
	v_fmac_f32_e32 v102, v58, v12
	v_fmac_f32_e32 v14, v44, v32
	v_fmac_f32_e32 v102, v59, v13
	v_fmac_f32_e32 v15, v45, v32
	v_fmac_f32_e32 v102, v60, v14
	v_fmac_f32_e32 v102, v61, v15
	ds_write_b32 v118, v102 offset:10496
	s_waitcnt lgkmcnt(1)
	ds_read_b128 v[38:41], v0 offset:4608
	ds_read_b128 v[42:45], v0 offset:4624
	ds_read_b128 v[54:57], v0 offset:6656
	ds_read_b128 v[58:61], v0 offset:6672
	ds_read_b32 v32, v1 offset:8480
	v_fmac_f32_e32 v8, v22, v30
	v_fmac_f32_e32 v9, v23, v30
	v_mul_f32_e32 v36, v46, v8
	s_waitcnt vmcnt(10)
	v_fmac_f32_e32 v10, v24, v30
	v_fmac_f32_e32 v36, v47, v9
	v_fmac_f32_e32 v11, v25, v30
	v_lshlrev_b32_e32 v94, 16, v66
	v_fmac_f32_e32 v36, v48, v10
	v_fmac_f32_e32 v12, v26, v30
	v_fmac_f32_e32 v36, v49, v11
	v_and_b32_e32 v95, 0xffff0000, v66
	v_fmac_f32_e32 v13, v27, v30
	v_fmac_f32_e32 v36, v50, v12
	v_fmac_f32_e32 v14, v28, v30
	v_lshlrev_b32_e32 v96, 16, v67
	v_fmac_f32_e32 v36, v51, v13
	v_fmac_f32_e32 v15, v29, v30
	v_fmac_f32_e32 v36, v52, v14
	v_and_b32_e32 v97, 0xffff0000, v67
	v_fmac_f32_e32 v36, v53, v15
	ds_write_b32 v118, v36 offset:10752
	ds_write_b128 v2, v[94:97] offset:0
	v_lshlrev_b32_e32 v98, 16, v68
	s_waitcnt lgkmcnt(2)
	ds_read_b128 v[22:25], v0 offset:4864
	ds_read_b128 v[26:29], v0 offset:4880
	ds_read_b128 v[46:49], v0 offset:6912
	ds_read_b128 v[50:53], v0 offset:6928
	ds_read_b32 v30, v1 offset:8512
	v_fmac_f32_e32 v8, v38, v32
	v_fmac_f32_e32 v9, v39, v32
	v_mul_f32_e32 v102, v54, v8
	v_and_b32_e32 v99, 0xffff0000, v68
	v_fmac_f32_e32 v10, v40, v32
	v_fmac_f32_e32 v102, v55, v9
	v_fmac_f32_e32 v11, v41, v32
	v_lshlrev_b32_e32 v100, 16, v69
	v_fmac_f32_e32 v102, v56, v10
	v_fmac_f32_e32 v12, v42, v32
	v_fmac_f32_e32 v102, v57, v11
	v_and_b32_e32 v101, 0xffff0000, v69
	v_fmac_f32_e32 v13, v43, v32
	v_fmac_f32_e32 v102, v58, v12
	v_fmac_f32_e32 v14, v44, v32
	ds_write_b128 v2, v[98:101] offset:16
	v_fmac_f32_e32 v102, v59, v13
	v_fmac_f32_e32 v15, v45, v32
	v_fmac_f32_e32 v102, v60, v14
	v_lshlrev_b32_e32 v94, 16, v62
	v_fmac_f32_e32 v102, v61, v15
	ds_write_b32 v118, v102 offset:11008
	v_and_b32_e32 v95, 0xffff0000, v62
	v_lshlrev_b32_e32 v96, 16, v63
	s_waitcnt lgkmcnt(2)
	ds_read_b128 v[38:41], v0 offset:5120
	ds_read_b128 v[42:45], v0 offset:5136
	ds_read_b128 v[54:57], v0 offset:7168
	ds_read_b128 v[58:61], v0 offset:7184
	ds_read_b32 v32, v1 offset:8544
	v_fmac_f32_e32 v8, v22, v30
	v_fmac_f32_e32 v9, v23, v30
	v_mul_f32_e32 v36, v46, v8
	v_and_b32_e32 v97, 0xffff0000, v63
	v_fmac_f32_e32 v10, v24, v30
	v_fmac_f32_e32 v36, v47, v9
	v_fmac_f32_e32 v11, v25, v30
	ds_write_b128 v2, v[94:97] offset:2048
	v_fmac_f32_e32 v36, v48, v10
	v_fmac_f32_e32 v12, v26, v30
	v_fmac_f32_e32 v36, v49, v11
	v_lshlrev_b32_e32 v98, 16, v64
	v_fmac_f32_e32 v13, v27, v30
	v_fmac_f32_e32 v36, v50, v12
	v_fmac_f32_e32 v14, v28, v30
	v_and_b32_e32 v99, 0xffff0000, v64
	v_fmac_f32_e32 v36, v51, v13
	v_fmac_f32_e32 v15, v29, v30
	v_fmac_f32_e32 v36, v52, v14
	v_lshlrev_b32_e32 v100, 16, v65
	v_fmac_f32_e32 v36, v53, v15
	ds_write_b32 v118, v36 offset:11264
	v_and_b32_e32 v101, 0xffff0000, v65
	ds_write_b128 v2, v[98:101] offset:2064
	s_waitcnt lgkmcnt(3)
	ds_read_b128 v[22:25], v0 offset:5376
	ds_read_b128 v[26:29], v0 offset:5392
	ds_read_b128 v[46:49], v0 offset:7424
	ds_read_b128 v[50:53], v0 offset:7440
	ds_read_b32 v30, v1 offset:8576
	v_fmac_f32_e32 v8, v38, v32
	v_fmac_f32_e32 v9, v39, v32
	v_mul_f32_e32 v102, v54, v8
	s_waitcnt vmcnt(9)
	v_fmac_f32_e32 v10, v40, v32
	v_fmac_f32_e32 v102, v55, v9
	v_fmac_f32_e32 v11, v41, v32
	v_lshlrev_b32_e32 v31, 16, v31
	v_fmac_f32_e32 v102, v56, v10
	v_fmac_f32_e32 v12, v42, v32
	v_fmac_f32_e32 v102, v57, v11
	v_mul_f32_e32 v31, v103, v31
	v_fmac_f32_e32 v13, v43, v32
	v_fmac_f32_e32 v102, v58, v12
	v_fmac_f32_e32 v14, v44, v32
	s_nop 0
	v_fmac_f32_e32 v102, v59, v13
	v_fmac_f32_e32 v15, v45, v32
	v_fmac_f32_e32 v102, v60, v14
	ds_write_b32 v4, v31 offset:4096
	v_fmac_f32_e32 v102, v61, v15
	ds_write_b32 v118, v102 offset:11520
	s_waitcnt lgkmcnt(2)
	ds_read_b128 v[38:41], v0 offset:5632
	ds_read_b128 v[42:45], v0 offset:5648
	ds_read_b128 v[54:57], v0 offset:7680
	ds_read_b128 v[58:61], v0 offset:7696
	ds_read_b32 v32, v1 offset:8608
	v_fmac_f32_e32 v8, v22, v30
	v_fmac_f32_e32 v9, v23, v30
	v_mul_f32_e32 v36, v46, v8
	global_load_dwordx4 v[62:65], v5, s[94:95]
	global_load_dwordx4 v[66:69], v5, s[94:95] offset:512
	global_load_ushort v31, v6, s[94:95]
	v_add_u32_e32 v5, 0x6800, v5
	v_add_u32_e32 v6, 0x10000, v6
	v_fmac_f32_e32 v10, v24, v30
	v_fmac_f32_e32 v36, v47, v9
	v_fmac_f32_e32 v11, v25, v30
	ds_read_b128 v[124:127], v119 offset:8704
	v_fmac_f32_e32 v36, v48, v10
	v_fmac_f32_e32 v12, v26, v30
	v_fmac_f32_e32 v36, v49, v11
	ds_read_b128 v[128:131], v120 offset:8704
	v_fmac_f32_e32 v13, v27, v30
	v_fmac_f32_e32 v36, v50, v12
	v_fmac_f32_e32 v14, v28, v30
	v_fmac_f32_e32 v36, v51, v13
	v_fmac_f32_e32 v15, v29, v30
	v_fmac_f32_e32 v36, v52, v14
	v_fmac_f32_e32 v36, v53, v15
	ds_write_b32 v118, v36 offset:11776
	s_waitcnt lgkmcnt(3)
	ds_read_b128 v[22:25], v0 offset:5888
	ds_read_b128 v[26:29], v0 offset:5904
	ds_read_b128 v[46:49], v0 offset:7936
	ds_read_b128 v[50:53], v0 offset:7952
	ds_read_b32 v30, v1 offset:8640
	v_fmac_f32_e32 v8, v38, v32
	v_fmac_f32_e32 v9, v39, v32
	v_mul_f32_e32 v102, v54, v8
	v_fmac_f32_e32 v10, v40, v32
	v_fmac_f32_e32 v102, v55, v9
	v_fmac_f32_e32 v11, v41, v32
	v_fmac_f32_e32 v102, v56, v10
	v_fmac_f32_e32 v12, v42, v32
	v_fmac_f32_e32 v102, v57, v11
	v_fmac_f32_e32 v13, v43, v32
	v_fmac_f32_e32 v102, v58, v12
	v_fmac_f32_e32 v14, v44, v32
	v_fmac_f32_e32 v102, v59, v13
	v_fmac_f32_e32 v15, v45, v32
	v_fmac_f32_e32 v102, v60, v14
	v_fmac_f32_e32 v102, v61, v15
	ds_write_b32 v118, v102 offset:12032
	s_waitcnt lgkmcnt(1)
	ds_read_b128 v[38:41], v0 offset:6144
	ds_read_b128 v[42:45], v0 offset:6160
	ds_read_b128 v[54:57], v0 offset:8192
	ds_read_b128 v[58:61], v0 offset:8208
	ds_read_b32 v32, v1 offset:8672
	v_fmac_f32_e32 v8, v22, v30
	v_fmac_f32_e32 v9, v23, v30
	v_mul_f32_e32 v36, v46, v8
	s_waitcnt lgkmcnt(12)
	v_fmac_f32_e32 v10, v24, v30
	v_fmac_f32_e32 v36, v47, v9
	v_fmac_f32_e32 v11, v25, v30
	v_add_f32_e32 v124, v124, v128
	v_fmac_f32_e32 v36, v48, v10
	v_fmac_f32_e32 v12, v26, v30
	v_fmac_f32_e32 v36, v49, v11
	v_add_f32_e32 v125, v125, v129
	v_fmac_f32_e32 v13, v27, v30
	v_fmac_f32_e32 v36, v50, v12
	v_fmac_f32_e32 v14, v28, v30
	v_add_f32_e32 v126, v126, v130
	v_fmac_f32_e32 v36, v51, v13
	v_fmac_f32_e32 v15, v29, v30
	v_fmac_f32_e32 v36, v52, v14
	v_add_f32_e32 v127, v127, v131
	v_fmac_f32_e32 v36, v53, v15
	ds_write_b32 v118, v36 offset:12288
	v_add_f32_e32 v124, v124, v125
	v_add_f32_e32 v126, v126, v127
	v_add_f32_e32 v124, v124, v126
	v_mul_f32_e32 v124, v109, v124
	v_cvt_pk_bf16_f32 v21, v124, v124
	ds_write_b16 v112, v21 offset:13568
	s_waitcnt lgkmcnt(2)
	ds_read_b128 v[22:25], v0 offset:0
	ds_read_b128 v[26:29], v0 offset:16
	ds_read_b128 v[46:49], v0 offset:2048
	ds_read_b128 v[50:53], v0 offset:2064
	ds_read_b32 v30, v1 offset:4096
	v_fmac_f32_e32 v8, v38, v32
	v_fmac_f32_e32 v9, v39, v32
	v_mul_f32_e32 v102, v54, v8
	v_fmac_f32_e32 v10, v40, v32
	v_fmac_f32_e32 v102, v55, v9
	v_fmac_f32_e32 v11, v41, v32
	v_fmac_f32_e32 v102, v56, v10
	v_fmac_f32_e32 v12, v42, v32
	v_fmac_f32_e32 v102, v57, v11
	v_fmac_f32_e32 v13, v43, v32
	v_fmac_f32_e32 v102, v58, v12
	v_fmac_f32_e32 v14, v44, v32
	v_fmac_f32_e32 v102, v59, v13
	v_fmac_f32_e32 v15, v45, v32
	v_fmac_f32_e32 v102, v60, v14
	v_fmac_f32_e32 v102, v61, v15
	ds_write_b32 v118, v102 offset:12544
	v_mul_f32_e32 v8, s44, v8
	v_mul_f32_e32 v9, s44, v9
	v_mul_f32_e32 v10, s44, v10
	v_mul_f32_e32 v11, s44, v11
	v_mul_f32_e32 v12, s44, v12
	v_mul_f32_e32 v13, s44, v13
	v_mul_f32_e32 v14, s44, v14
	v_mul_f32_e32 v15, s44, v15
	s_sleep 6
	s_sub_u32 s12, s12, 1
	s_cmp_lg_u32 s12, 0
	s_cbranch_scc1 .Lls0_8_loop
	ds_read_b128 v[124:127], v119 offset:10752
	ds_read_b128 v[128:131], v120 offset:10752
	s_waitcnt lgkmcnt(0)
	v_add_f32_e32 v124, v124, v128
	v_add_f32_e32 v125, v125, v129
	v_add_f32_e32 v126, v126, v130
	v_add_f32_e32 v127, v127, v131
	v_add_f32_e32 v124, v124, v125
	v_add_f32_e32 v126, v126, v127
	v_add_f32_e32 v124, v124, v126
	v_mul_f32_e32 v124, v110, v124
	v_cvt_pk_bf16_f32 v21, v124, v124
	ds_write_b16 v112, v21 offset:13696
	s_waitcnt lgkmcnt(0)
	ds_read_b128 v[114:117], v113 offset:13312
	s_waitcnt lgkmcnt(0)
	global_store_dwordx4 v7, v[114:117], s[94:95]
	v_add_u32_e32 v7, 0x20000, v7
	s_nop 0
	ds_read_b128 v[114:117], v113 offset:14336
	s_waitcnt lgkmcnt(0)
	global_store_dwordx4 v7, v[114:117], s[94:95]
	v_add_u32_e32 v7, 0x20000, v7
	s_nop 0
	ds_read_b128 v[114:117], v113 offset:15360
	s_waitcnt lgkmcnt(0)
	global_store_dwordx4 v7, v[114:117], s[94:95]
	v_add_u32_e32 v7, 0x20000, v7
	s_nop 0
	ds_read_b128 v[114:117], v113 offset:16384
	s_waitcnt lgkmcnt(0)
	global_store_dwordx4 v7, v[114:117], s[94:95]
	v_add_u32_e32 v7, 0x20000, v7
	s_nop 0
	ds_read_b128 v[114:117], v113 offset:17408
	s_waitcnt lgkmcnt(0)
	global_store_dwordx4 v7, v[114:117], s[94:95]
	v_add_u32_e32 v7, 0x20000, v7
	s_nop 0
	ds_read_b128 v[114:117], v113 offset:18432
	s_waitcnt lgkmcnt(0)
	global_store_dwordx4 v7, v[114:117], s[94:95]
	v_add_u32_e32 v7, 0x20000, v7
	s_nop 0
	ds_read_b128 v[114:117], v113 offset:19456
	s_waitcnt lgkmcnt(0)
	global_store_dwordx4 v7, v[114:117], s[94:95]
	v_add_u32_e32 v7, 0x20000, v7
	s_nop 0
	ds_read_b128 v[114:117], v113 offset:20480
	s_waitcnt lgkmcnt(0)
	global_store_dwordx4 v7, v[114:117], s[94:95]
	v_add_u32_e32 v7, 0x20000, v7
	s_nop 0
	global_store_dword v111, v8, s[26:27] offset:0
	global_store_dword v111, v9, s[26:27] offset:256
	global_store_dword v111, v10, s[26:27] offset:512
	global_store_dword v111, v11, s[26:27] offset:768
	global_store_dword v111, v12, s[26:27] offset:1024
	global_store_dword v111, v13, s[26:27] offset:1280
	global_store_dword v111, v14, s[26:27] offset:1536
	global_store_dword v111, v15, s[26:27] offset:1792
	s_waitcnt vmcnt(0) lgkmcnt(0)
	s_setprio 0
	s_branch .Lls_done
